# ssm pass 3: unit's u rows touched once up front so the scan's row loads hit L2; state update as four FMAs per step
# speedup vs baseline: 1.0014x; 1.0014x over previous
; #define LAS __attribute__((address_space(3)))
; __device__ __forceinline__ void ssm_pass3h(CArgs* ap, const float* COEF, int l, const bf16_t* PROJ, const float* SST, bf16_t* YS, LAS unsigned char* wlds, int unit, int lane) {
;     ...
;     for (int j = 0; j < 8; ++j) {
;         const int k0 = 16 * j + 4 * fq;
;         const float* src = (j < 4 ? ap->in[16] : ap->in[17]) + ((size_t)(l * 32 + g) * 16 + fr) * 64 + (j < 4 ? k0 : k0 - 64);
;         const f32x4 c4 = *(const f32x4*)src;
; #pragma unroll
;         for (int r = 0; r < 4; ++r) cmB[4 * j + r] = (j < 4) ? c4[r] : -c4[r];
;     }
;     const float dsk = ap->in[18][l * 512 + g * 16 + fr];
;     float tr = abr, ti = abi;
; #pragma unroll
;     for (int k = 0; k < 7; ++k) { const float nr = tr * tr - ti * ti, ni = 2.f * tr * ti; tr = nr; ti = ni; }
;     float hr = 0.f, hi = 0.f;
;     const float* sp = SST + ((size_t)(unit - c) * 64 + lane) * 2;
;     int cc = 0;
;     for (; cc + 8 <= c; cc += 8) {
;         float2 s8[8];
; #pragma unroll
;         for (int j = 0; j < 8; ++j) s8[j] = *(const float2*)(sp + (size_t)(cc + j) * 128);
; #pragma unroll
;         for (int j = 0; j < 8; ++j) { const float nr = tr * hr - ti * hi + s8[j].x, ni = tr * hi + ti * hr + s8[j].y; hr = nr; hi = ni; }
;     }
;     for (; cc < c; ++cc) { const float2 s = *(const float2*)(sp + (size_t)cc * 128); const float nr = tr * hr - ti * hi + s.x, ni = tr * hi + ti * hr + s.y; hr = nr; hi = ni; }
;     const size_t row0 = (size_t)(b * SEQ + c * 128);
;     const bf16_t* up = PROJ + row0 * INW + 2560 + g * 16;
;     LAS float* Hf = (LAS float*)wlds;
;     u32x4 wn[8];
; #pragma unroll
;     for (int tt = 0; tt < 4; ++tt) { wn[2 * tt] = ((const u32x4*)(up + (size_t)tt * INW))[0]; wn[2 * tt + 1] = ((const u32x4*)(up + (size_t)tt * INW))[1]; }
.LBB0_148:
	s_lshl_b32 s0, s9, 2
	s_and_b32 s0, s0, 0xffffe000
	s_lshl_b32 s1, s3, 7
	s_or_b32 s0, s0, s1
	s_ashr_i32 s1, s0, 31
	s_mul_i32 s10, s0, 0x4800
	s_mul_hi_i32 s3, s0, 0x4800
	s_add_u32 s10, s68, s10
	s_addc_u32 s3, s69, s3
	s_lshl_b32 s78, s2, 1
	s_add_u32 s10, s10, s78
	s_addc_u32 s11, s3, 0
	s_add_u32 s2, s10, 0x1400
	s_addc_u32 s3, s11, 0
	s_add_u32 s12, s10, 0x5c00
	v_mov_b32_e32 v0, 0x5000
	v_and_b32_e32 v224, 3, v166
	v_mul_u32_u24_e32 v224, 0x4800, v224
	v_mul_u32_u24_e32 v226, 0x4800, v166
	v_add_u32_e32 v227, 0x120000, v226
	global_load_dword v225, v226, s[2:3]
	global_load_dword v225, v227, s[2:3]
	v_mov_b32_e32 v208, v101
	v_mov_b32_e32 v209, v103
	v_mov_b32_e32 v210, v102
	v_mov_b32_e32 v211, v104
	v_mov_b32_e32 v212, v105
	v_mov_b32_e32 v213, v107
	v_mov_b32_e32 v214, v106
	v_mov_b32_e32 v215, v108
	v_mov_b32_e32 v216, v109
	v_mov_b32_e32 v217, v111
	v_mov_b32_e32 v218, v110
	v_mov_b32_e32 v219, v112
	v_mov_b32_e32 v220, v113
	v_mov_b32_e32 v221, v115
	v_mov_b32_e32 v222, v114
	v_mov_b32_e32 v223, v116
	global_load_dwordx4 v[20:23], v224, s[2:3] offset:16
	global_load_dwordx4 v[24:27], v224, s[2:3]
	s_add_u32 s12, s2, 0x12000
	s_addc_u32 s13, s3, 0
	global_load_dwordx4 v[28:31], v224, s[12:13] offset:16
	global_load_dwordx4 v[32:35], v224, s[12:13]
	s_add_u32 s12, s2, 0x24000
	s_addc_u32 s13, s3, 0
	global_load_dwordx4 v[36:39], v224, s[12:13] offset:16
	global_load_dwordx4 v[40:43], v224, s[12:13]
	s_add_u32 s12, s2, 0x36000
	s_addc_u32 s13, s3, 0
	global_load_dwordx4 v[44:47], v224, s[12:13] offset:16
	global_load_dwordx4 v[48:51], v224, s[12:13]
	v_lshl_add_u64 v[92:93], v[80:81], 0, s[78:79]
	v_pk_mov_b32 v[94:95], v[2:3], v[2:3] op_sel:[1,0]
	s_mov_b32 s10, 0
	s_waitcnt vmcnt(12)
	v_xor_b32_e32 v89, 0x80000000, v64
	v_xor_b32_e32 v117, 0x80000000, v65
	v_xor_b32_e32 v118, 0x80000000, v66
	v_xor_b32_e32 v119, 0x80000000, v67
	s_waitcnt vmcnt(11)
	v_xor_b32_e32 v120, 0x80000000, v60
	v_xor_b32_e32 v121, 0x80000000, v61
	v_xor_b32_e32 v122, 0x80000000, v62
	v_xor_b32_e32 v123, 0x80000000, v63
	s_waitcnt vmcnt(10)
	v_xor_b32_e32 v124, 0x80000000, v56
	v_xor_b32_e32 v125, 0x80000000, v57
	v_xor_b32_e32 v126, 0x80000000, v58
	v_xor_b32_e32 v127, 0x80000000, v59
	s_waitcnt vmcnt(9)
	v_xor_b32_e32 v128, 0x80000000, v52
	v_xor_b32_e32 v129, 0x80000000, v53
	v_xor_b32_e32 v130, 0x80000000, v54
	v_xor_b32_e32 v131, 0x80000000, v55
	s_mov_b32 s11, 0
	s_waitcnt vmcnt(0)

; __device__ __forceinline__ void ssm_pass3h(CArgs* ap, const float* COEF, int l, const bf16_t* PROJ, const float* SST, bf16_t* YS, LAS unsigned char* wlds, int unit, int lane) {
;     ...
;         for (int q = 0; q < 4; ++q) {
;             const int t = 16 * blk + 4 * q;
;             u32x4 wc[8];
; #pragma unroll
;             for (int j = 0; j < 8; ++j) wc[j] = wn[j];
;             const int tn = (t + 4 < 128) ? t + 4 : t;
; #pragma unroll
;             for (int tt = 0; tt < 4; ++tt) { wn[2 * tt] = ((const u32x4*)(up + (size_t)(tn + tt) * INW))[0]; wn[2 * tt + 1] = ((const u32x4*)(up + (size_t)(tn + tt) * INW))[1]; }
; #pragma unroll
;             for (int tt = 0; tt < 4; ++tt) {
;                 const u32x4 w0 = wc[2 * tt], w1 = wc[2 * tt + 1];
;                 const unsigned u2[8] = {w0.x, w0.y, w0.z, w0.w, w1.x, w1.y, w1.z, w1.w};
;                 float br_ = 0.f, bi_ = 0.f;
; #pragma unroll
;                 for (int k = 0; k < 8; ++k) { br_ = __builtin_amdgcn_fdot2_f32_bf16(__builtin_bit_cast(bf16x2v, bbr2[k]), __builtin_bit_cast(bf16x2v, u2[k]), br_, false);
;                                                bi_ = __builtin_amdgcn_fdot2_f32_bf16(__builtin_bit_cast(bf16x2v, bbi2[k]), __builtin_bit_cast(bf16x2v, u2[k]), bi_, false); }
;                 const float nr = abr * hr - abi * hi + br_, ni = abr * hi + abi * hr + bi_; hr = nr; hi = ni;
;                 Hf[(4 * q + tt) * 132 + lane] = hr; Hf[(4 * q + tt) * 132 + 64 + lane] = hi;
;             }
.LBB0_150:
	s_add_i32 s13, s14, 4
	s_add_i32 s78, s14, 16
	s_cmpk_lt_u32 s14, 0x70
	s_cselect_b32 s78, s78, s14
	s_mul_i32 s78, s78, 0x2400
	s_lshl_b64 s[14:15], s[78:79], 1
	s_add_u32 s14, s2, s14
	s_addc_u32 s15, s3, s15
	s_waitcnt vmcnt(14)
	v_mfma_f32_4x4x4_16b_bf16 v[144:147], v[24:25], v[208:209], 0
	v_mfma_f32_4x4x4_16b_bf16 v[148:151], v[24:25], v[210:211], 0
	s_nop 0
	v_mfma_f32_4x4x4_16b_bf16 v[144:147], v[26:27], v[212:213], v[144:147]
	v_mfma_f32_4x4x4_16b_bf16 v[148:151], v[26:27], v[214:215], v[148:151]
	s_nop 0
	v_mfma_f32_4x4x4_16b_bf16 v[144:147], v[20:21], v[216:217], v[144:147]
	v_mfma_f32_4x4x4_16b_bf16 v[148:151], v[20:21], v[218:219], v[148:151]
	s_nop 0
	v_mfma_f32_4x4x4_16b_bf16 v[144:147], v[22:23], v[220:221], v[144:147]
	v_mfma_f32_4x4x4_16b_bf16 v[148:151], v[22:23], v[222:223], v[148:151]
	s_nop 0
	global_load_dwordx4 v[20:23], v224, s[14:15] offset:16
	global_load_dwordx4 v[24:27], v224, s[14:15]
	v_add_u32_e32 v97, s12, v99
	v_add_u32_e32 v184, 32, v97
	v_add_u32_e32 v185, 48, v97
	v_fma_f32 v152, -v3, v91, v144
	v_fma_f32 v153, v3, v90, v148
	v_fma_f32 v90, v2, v90, v152
	v_fma_f32 v91, v2, v91, v153
	ds_write2st64_b32 v97, v90, v91 offset1:1
	v_fma_f32 v152, -v3, v91, v145
	v_fma_f32 v153, v3, v90, v149
	v_fma_f32 v90, v2, v90, v152
	v_fma_f32 v91, v2, v91, v153
	ds_write2_b32 v97, v90, v91 offset0:132 offset1:196
	v_fma_f32 v152, -v3, v91, v146
	v_fma_f32 v153, v3, v90, v150
	v_fma_f32 v90, v2, v90, v152
	v_fma_f32 v91, v2, v91, v153
	ds_write2st64_b32 v184, v90, v91 offset0:4 offset1:5
	v_fma_f32 v152, -v3, v91, v147
	v_fma_f32 v153, v3, v90, v151
	v_fma_f32 v90, v2, v90, v152
	v_fma_f32 v91, v2, v91, v153
	ds_write2st64_b32 v185, v90, v91 offset0:6 offset1:7
	s_addk_i32 s12, 0x840
	s_mov_b32 s14, s13
	s_add_i32 s13, s14, 4
	s_add_i32 s78, s14, 16
	s_cmpk_lt_u32 s14, 0x70
	s_cselect_b32 s78, s78, s14
	s_mul_i32 s78, s78, 0x2400
	s_lshl_b64 s[14:15], s[78:79], 1
	s_add_u32 s14, s2, s14
	s_addc_u32 s15, s3, s15
	s_waitcnt vmcnt(14)
	v_mfma_f32_4x4x4_16b_bf16 v[144:147], v[32:33], v[208:209], 0
	v_mfma_f32_4x4x4_16b_bf16 v[148:151], v[32:33], v[210:211], 0
	s_nop 0
	v_mfma_f32_4x4x4_16b_bf16 v[144:147], v[34:35], v[212:213], v[144:147]
	v_mfma_f32_4x4x4_16b_bf16 v[148:151], v[34:35], v[214:215], v[148:151]
	s_nop 0
	v_mfma_f32_4x4x4_16b_bf16 v[144:147], v[28:29], v[216:217], v[144:147]
	v_mfma_f32_4x4x4_16b_bf16 v[148:151], v[28:29], v[218:219], v[148:151]
	s_nop 0
	v_mfma_f32_4x4x4_16b_bf16 v[144:147], v[30:31], v[220:221], v[144:147]
	v_mfma_f32_4x4x4_16b_bf16 v[148:151], v[30:31], v[222:223], v[148:151]
	s_nop 0
	global_load_dwordx4 v[28:31], v224, s[14:15] offset:16
	global_load_dwordx4 v[32:35], v224, s[14:15]
	v_add_u32_e32 v97, s12, v99
	v_add_u32_e32 v184, 32, v97
	v_add_u32_e32 v185, 48, v97
	v_fma_f32 v152, -v3, v91, v144
	v_fma_f32 v153, v3, v90, v148
	v_fma_f32 v90, v2, v90, v152
	v_fma_f32 v91, v2, v91, v153
	ds_write2st64_b32 v97, v90, v91 offset1:1
	v_fma_f32 v152, -v3, v91, v145
	v_fma_f32 v153, v3, v90, v149
	v_fma_f32 v90, v2, v90, v152
	v_fma_f32 v91, v2, v91, v153
	ds_write2_b32 v97, v90, v91 offset0:132 offset1:196
	v_fma_f32 v152, -v3, v91, v146
	v_fma_f32 v153, v3, v90, v150
	v_fma_f32 v90, v2, v90, v152
	v_fma_f32 v91, v2, v91, v153
	ds_write2st64_b32 v184, v90, v91 offset0:4 offset1:5
	v_fma_f32 v152, -v3, v91, v147
	v_fma_f32 v153, v3, v90, v151
	v_fma_f32 v90, v2, v90, v152
	v_fma_f32 v91, v2, v91, v153
	ds_write2st64_b32 v185, v90, v91 offset0:6 offset1:7
	s_addk_i32 s12, 0x840
	s_mov_b32 s14, s13
	s_add_i32 s13, s14, 4
	s_add_i32 s78, s14, 16
	s_cmpk_lt_u32 s14, 0x70
	s_cselect_b32 s78, s78, s14
	s_mul_i32 s78, s78, 0x2400
	s_lshl_b64 s[14:15], s[78:79], 1
	s_add_u32 s14, s2, s14
	s_addc_u32 s15, s3, s15
	s_waitcnt vmcnt(14)
	v_mfma_f32_4x4x4_16b_bf16 v[144:147], v[40:41], v[208:209], 0
	v_mfma_f32_4x4x4_16b_bf16 v[148:151], v[40:41], v[210:211], 0
	s_nop 0
	v_mfma_f32_4x4x4_16b_bf16 v[144:147], v[42:43], v[212:213], v[144:147]
	v_mfma_f32_4x4x4_16b_bf16 v[148:151], v[42:43], v[214:215], v[148:151]
	s_nop 0
	v_mfma_f32_4x4x4_16b_bf16 v[144:147], v[36:37], v[216:217], v[144:147]
	v_mfma_f32_4x4x4_16b_bf16 v[148:151], v[36:37], v[218:219], v[148:151]
	s_nop 0
	v_mfma_f32_4x4x4_16b_bf16 v[144:147], v[38:39], v[220:221], v[144:147]
	v_mfma_f32_4x4x4_16b_bf16 v[148:151], v[38:39], v[222:223], v[148:151]
	s_nop 0
	global_load_dwordx4 v[36:39], v224, s[14:15] offset:16
	global_load_dwordx4 v[40:43], v224, s[14:15]
	v_add_u32_e32 v97, s12, v99
	v_add_u32_e32 v184, 32, v97
	v_add_u32_e32 v185, 48, v97
	v_fma_f32 v152, -v3, v91, v144
	v_fma_f32 v153, v3, v90, v148
	v_fma_f32 v90, v2, v90, v152
	v_fma_f32 v91, v2, v91, v153
	ds_write2st64_b32 v97, v90, v91 offset1:1
	v_fma_f32 v152, -v3, v91, v145
	v_fma_f32 v153, v3, v90, v149
	v_fma_f32 v90, v2, v90, v152
	v_fma_f32 v91, v2, v91, v153
	ds_write2_b32 v97, v90, v91 offset0:132 offset1:196
	v_fma_f32 v152, -v3, v91, v146
	v_fma_f32 v153, v3, v90, v150
	v_fma_f32 v90, v2, v90, v152
	v_fma_f32 v91, v2, v91, v153
	ds_write2st64_b32 v184, v90, v91 offset0:4 offset1:5
	v_fma_f32 v152, -v3, v91, v147
	v_fma_f32 v153, v3, v90, v151
	v_fma_f32 v90, v2, v90, v152
	v_fma_f32 v91, v2, v91, v153
	ds_write2st64_b32 v185, v90, v91 offset0:6 offset1:7
	s_addk_i32 s12, 0x840
	s_mov_b32 s14, s13
	s_add_i32 s13, s14, 4
	s_add_i32 s78, s14, 16
	s_cmpk_lt_u32 s14, 0x70
	s_cselect_b32 s78, s78, s14
	s_mul_i32 s78, s78, 0x2400
	s_lshl_b64 s[14:15], s[78:79], 1
	s_add_u32 s14, s2, s14
	s_addc_u32 s15, s3, s15
	s_waitcnt vmcnt(14)
; __device__ __forceinline__ float gelu_t(float x) { const float p = __builtin_fmaf(x * x, -0.10294324f, -2.30220819f); return x * __builtin_amdgcn_rcpf(1.f + __builtin_amdgcn_exp2f(x * p)); }
; #define LAS __attribute__((address_space(3)))
; __device__ __forceinline__ unsigned f2bf(float f) { unsigned u = __builtin_bit_cast(unsigned, f); return (u + 0x7fffu + ((u >> 16) & 1u)) >> 16; }
; __device__ __forceinline__ void ssm_pass3h(CArgs* ap, const float* COEF, int l, const bf16_t* PROJ, const float* SST, bf16_t* YS, LAS unsigned char* wlds, int unit, int lane) {
;     ...
;                 const float nr = abr * hr - abi * hi + br_, ni = abr * hi + abi * hr + bi_; hr = nr; hi = ni;
;                 Hf[(4 * q + tt) * 132 + lane] = hr; Hf[(4 * q + tt) * 132 + 64 + lane] = hi;
;             }
;         }
;         asm volatile("s_waitcnt lgkmcnt(0)" ::: "memory");
;         f32x4 y = (f32x4){0.f, 0.f, 0.f, 0.f};
; #pragma unroll
;         for (int j = 0; j < 8; ++j) {
;             const f32x4 a4 = *(const LAS f32x4*)(Hf + fr * 132 + 16 * j + 4 * fq);
; #pragma unroll
;             for (int r = 0; r < 4; ++r) y = __builtin_amdgcn_mfma_f32_16x16x4f32(a4[r], cmB[4 * j + r], y, 0, 0, 0);
;         }
;         asm volatile("s_waitcnt lgkmcnt(0)" ::: "memory");
; #pragma unroll
;         for (int i = 0; i < 4; ++i) {
;             const size_t row = row0 + 16 * blk + 4 * fq + i;
;             YS[row * 512 + g * 16 + fr] = (bf16_t)f2bf(gelu_t(y[i] + dsk * __uint_as_float(((unsigned)uq[i]) << 16)));
;         }
	v_mfma_f32_4x4x4_16b_bf16 v[144:147], v[48:49], v[208:209], 0
	v_mfma_f32_4x4x4_16b_bf16 v[148:151], v[48:49], v[210:211], 0
	s_nop 0
	v_mfma_f32_4x4x4_16b_bf16 v[144:147], v[50:51], v[212:213], v[144:147]
	v_mfma_f32_4x4x4_16b_bf16 v[148:151], v[50:51], v[214:215], v[148:151]
	s_nop 0
	v_mfma_f32_4x4x4_16b_bf16 v[144:147], v[44:45], v[216:217], v[144:147]
	v_mfma_f32_4x4x4_16b_bf16 v[148:151], v[44:45], v[218:219], v[148:151]
	s_nop 0
	v_mfma_f32_4x4x4_16b_bf16 v[144:147], v[46:47], v[220:221], v[144:147]
	v_mfma_f32_4x4x4_16b_bf16 v[148:151], v[46:47], v[222:223], v[148:151]
	s_nop 0
	global_load_dwordx4 v[44:47], v224, s[14:15] offset:16
	global_load_dwordx4 v[48:51], v224, s[14:15]
	v_add_u32_e32 v97, s12, v99
	v_add_u32_e32 v184, 32, v97
	v_add_u32_e32 v185, 48, v97
	v_fma_f32 v152, -v3, v91, v144
	v_fma_f32 v153, v3, v90, v148
	v_fma_f32 v90, v2, v90, v152
	v_fma_f32 v91, v2, v91, v153
	ds_write2st64_b32 v97, v90, v91 offset1:1
	v_fma_f32 v152, -v3, v91, v145
	v_fma_f32 v153, v3, v90, v149
	v_fma_f32 v90, v2, v90, v152
	v_fma_f32 v91, v2, v91, v153
	ds_write2_b32 v97, v90, v91 offset0:132 offset1:196
	v_fma_f32 v152, -v3, v91, v146
	v_fma_f32 v153, v3, v90, v150
	v_fma_f32 v90, v2, v90, v152
	v_fma_f32 v91, v2, v91, v153
	ds_write2st64_b32 v184, v90, v91 offset0:4 offset1:5
	v_fma_f32 v152, -v3, v91, v147
	v_fma_f32 v153, v3, v90, v151
	v_fma_f32 v90, v2, v90, v152
	v_fma_f32 v91, v2, v91, v153
	ds_write2st64_b32 v185, v90, v91 offset0:6 offset1:7
	s_addk_i32 s12, 0x840
	s_mov_b32 s14, s13
	s_waitcnt lgkmcnt(0)
	ds_read_b128 v[144:147], v100
	ds_read_b128 v[148:151], v100 offset:64
	ds_read_b128 v[152:155], v100 offset:128
	ds_read_b128 v[168:171], v100 offset:192
	ds_read_b128 v[172:175], v100 offset:256
	ds_read_b128 v[176:179], v100 offset:320
	ds_read_b128 v[180:183], v100 offset:384
	ds_read_b128 v[184:187], v100 offset:448
	s_waitcnt vmcnt(11)
	v_lshlrev_b32_e32 v57, 16, v135
	v_mov_b32_e32 v97, v1
	v_or_b32_e32 v0, 1, v96
	v_or_b32_e32 v58, 2, v96
	v_mov_b32_e32 v59, v1
	v_or_b32_e32 v56, 3, v96
	s_add_i32 s11, s11, 1
	s_add_i32 s10, s10, 16
	s_cmp_eq_u32 s11, 8
	v_lshl_add_u64 v[60:61], v[96:97], 0, s[0:1]
	v_lshlrev_b64 v[60:61], 10, v[60:61]
	v_lshl_add_u64 v[60:61], v[92:93], 0, v[60:61]
	s_waitcnt lgkmcnt(6)
	v_mfma_f32_16x16x4_f32 v[52:55], v144, v4, 0
	v_mfma_f32_16x16x4_f32 v[188:191], v148, v8, 0
	v_mfma_f32_16x16x4_f32 v[52:55], v145, v5, v[52:55]
	v_mfma_f32_16x16x4_f32 v[188:191], v149, v9, v[188:191]
	v_mfma_f32_16x16x4_f32 v[52:55], v146, v6, v[52:55]
	v_mfma_f32_16x16x4_f32 v[188:191], v150, v10, v[188:191]
	v_mfma_f32_16x16x4_f32 v[52:55], v147, v7, v[52:55]
	v_mfma_f32_16x16x4_f32 v[188:191], v151, v11, v[188:191]
	s_waitcnt lgkmcnt(4)
	v_mfma_f32_16x16x4_f32 v[52:55], v152, v12, v[52:55]
	v_mfma_f32_16x16x4_f32 v[188:191], v168, v16, v[188:191]
	v_mfma_f32_16x16x4_f32 v[52:55], v153, v13, v[52:55]
	v_mfma_f32_16x16x4_f32 v[188:191], v169, v17, v[188:191]
	v_mfma_f32_16x16x4_f32 v[52:55], v154, v14, v[52:55]
	v_mfma_f32_16x16x4_f32 v[188:191], v170, v18, v[188:191]
	v_mfma_f32_16x16x4_f32 v[52:55], v155, v15, v[52:55]
	v_mfma_f32_16x16x4_f32 v[188:191], v171, v19, v[188:191]
	s_waitcnt lgkmcnt(2)
	v_mfma_f32_16x16x4_f32 v[52:55], v172, v89, v[52:55]
	v_mfma_f32_16x16x4_f32 v[188:191], v176, v120, v[188:191]
	v_mfma_f32_16x16x4_f32 v[52:55], v173, v117, v[52:55]
	v_mfma_f32_16x16x4_f32 v[188:191], v177, v121, v[188:191]
	v_mfma_f32_16x16x4_f32 v[52:55], v174, v118, v[52:55]
	v_mfma_f32_16x16x4_f32 v[188:191], v178, v122, v[188:191]
	v_mfma_f32_16x16x4_f32 v[52:55], v175, v119, v[52:55]
	v_mfma_f32_16x16x4_f32 v[188:191], v179, v123, v[188:191]
	s_waitcnt lgkmcnt(0)
	v_mfma_f32_16x16x4_f32 v[52:55], v180, v124, v[52:55]
	v_mfma_f32_16x16x4_f32 v[188:191], v184, v128, v[188:191]
	v_mfma_f32_16x16x4_f32 v[52:55], v181, v125, v[52:55]
	v_mfma_f32_16x16x4_f32 v[188:191], v185, v129, v[188:191]
	v_mfma_f32_16x16x4_f32 v[52:55], v182, v126, v[52:55]
	v_mfma_f32_16x16x4_f32 v[188:191], v186, v130, v[188:191]
	v_mfma_f32_16x16x4_f32 v[52:55], v183, v127, v[52:55]
	v_mfma_f32_16x16x4_f32 v[188:191], v187, v131, v[188:191]
	s_nop 9
	s_nop 1
	v_add_f32_e32 v52, v52, v188
	v_add_f32_e32 v53, v53, v189
	v_add_f32_e32 v54, v54, v190
	v_add_f32_e32 v55, v55, v191
	v_fma_f32 v52, v87, v57, v52
	v_mul_f32_e32 v57, v52, v52
	v_fmamk_f32 v57, v57, 0xbdd2d3e8, v196
	v_mul_f32_e32 v57, v52, v57
	v_exp_f32_e32 v57, v57
	s_nop 0
	v_add_f32_e32 v57, 1.0, v57
	v_rcp_f32_e32 v57, v57
	s_nop 0
	v_mul_f32_e32 v52, v52, v57
	v_bfe_u32 v57, v52, 16, 1
	v_add3_u32 v52, v52, v57, s80
	global_store_short_d16_hi v[60:61], v52, off
	v_lshl_add_u64 v[60:61], v[0:1], 0, s[0:1]
	s_waitcnt vmcnt(11)
	v_lshlrev_b32_e32 v0, 16, v134
	v_fma_f32 v0, v87, v0, v53
	v_mul_f32_e32 v52, v0, v0
	v_fmamk_f32 v52, v52, 0xbdd2d3e8, v196
	v_mul_f32_e32 v52, v0, v52
	v_exp_f32_e32 v52, v52
	v_mov_b32_e32 v57, v1
	v_add_f32_e32 v52, 1.0, v52
	v_rcp_f32_e32 v52, v52
	s_nop 0
	v_mul_f32_e32 v0, v0, v52
	v_bfe_u32 v52, v0, 16, 1
	v_add3_u32 v0, v0, v52, s80
	v_lshlrev_b64 v[52:53], 10, v[60:61]
	v_lshl_add_u64 v[52:53], v[92:93], 0, v[52:53]
	global_store_short_d16_hi v[52:53], v0, off
	s_waitcnt vmcnt(11)
	v_lshlrev_b32_e32 v0, 16, v133
	v_fma_f32 v0, v87, v0, v54
	v_mul_f32_e32 v54, v0, v0
	v_fmamk_f32 v54, v54, 0xbdd2d3e8, v196
	v_mul_f32_e32 v54, v0, v54
	v_exp_f32_e32 v54, v54
	v_lshl_add_u64 v[52:53], v[58:59], 0, s[0:1]
	v_lshlrev_b64 v[52:53], 10, v[52:53]
	v_lshl_add_u64 v[52:53], v[92:93], 0, v[52:53]
	v_add_f32_e32 v54, 1.0, v54
	v_rcp_f32_e32 v54, v54
	s_nop 0
	v_mul_f32_e32 v0, v0, v54
	v_bfe_u32 v54, v0, 16, 1
	v_add3_u32 v0, v0, v54, s80
	global_store_short_d16_hi v[52:53], v0, off
	s_waitcnt vmcnt(11)
	v_lshlrev_b32_e32 v0, 16, v132
	v_fmac_f32_e32 v55, v87, v0
	v_mul_f32_e32 v0, v55, v55
	v_fmamk_f32 v0, v0, 0xbdd2d3e8, v196
	v_mul_f32_e32 v0, v55, v0
	v_exp_f32_e32 v0, v0
	v_lshl_add_u64 v[52:53], v[56:57], 0, s[0:1]
	v_lshlrev_b64 v[52:53], 10, v[52:53]
	v_lshl_add_u64 v[52:53], v[92:93], 0, v[52:53]
	v_add_f32_e32 v0, 1.0, v0
	v_rcp_f32_e32 v0, v0
	s_nop 0
	v_mul_f32_e32 v0, v55, v0
	v_bfe_u32 v54, v0, 16, 1
	v_add3_u32 v0, v0, v54, s80
	global_store_short_d16_hi v[52:53], v0, off
	s_cbranch_scc0 .LBB0_149
	s_add_i32 s9, s9, s33
	s_cmpk_gt_i32 s9, 0xfff
	s_cbranch_scc0 .LBB0_141
